# GEMM accumulator clears between units use 64-bit moves (64 instead of 127 VALU instructions per clear)
# speedup vs baseline: 1.0070x; 1.0004x over previous
; template <class Epi, class Sched, bool ALIGN_EPI, bool LAST_FUSED = false, bool PERM = false, bool CARRY = false>
; __device__ __forceinline__ void gemm_phase(LAS unsigned char* lds, const int tid, const int K, const int lda, const int ldb, const Sched& S, const Epi& E) {
;     ...
; #pragma unroll
;         for (int a = 0; a < 2; ++a)
; #pragma unroll
;             for (int b = 0; b < 2; ++b)
; #pragma unroll
;                 for (int m = 0; m < 4; ++m)
; #pragma unroll
;                     for (int n = 0; n < 2; ++n) { if constexpr (CARRY) acc[a][b][m][n] = acc[a][b][m][n] * cs_; else acc[a][b][m][n] = (f32x4){0.f, 0.f, 0.f, 0.f}; }
;         cur = nxt; cA = nA; cB = nB; ++ui;
.LBB0_278:
	s_add_u32 s2, s2, 0x80080
	s_addc_u32 s3, s3, 0
	s_add_u32 s22, s4, 0x100
	v_mov_b32_e32 v2, 0
	s_addc_u32 s23, s5, 0
	s_mov_b32 s27, -2
	v_mov_b64_e32 v[2:3], 0
	v_mov_b64_e32 v[4:5], 0
	v_mov_b64_e32 v[6:7], 0
	v_mov_b64_e32 v[8:9], 0
	v_mov_b64_e32 v[10:11], 0
	v_mov_b64_e32 v[12:13], 0
	v_mov_b64_e32 v[14:15], 0
	v_mov_b64_e32 v[16:17], 0
	v_mov_b64_e32 v[18:19], 0
	v_mov_b64_e32 v[20:21], 0
	v_mov_b64_e32 v[22:23], 0
	v_mov_b64_e32 v[24:25], 0
	v_mov_b64_e32 v[26:27], 0
	v_mov_b64_e32 v[28:29], 0
	v_mov_b64_e32 v[30:31], 0
	v_mov_b64_e32 v[32:33], 0
	v_mov_b64_e32 v[34:35], 0
	v_mov_b64_e32 v[36:37], 0
	v_mov_b64_e32 v[38:39], 0
	v_mov_b64_e32 v[40:41], 0
	v_mov_b64_e32 v[42:43], 0
	v_mov_b64_e32 v[44:45], 0
	v_mov_b64_e32 v[46:47], 0
	v_mov_b64_e32 v[48:49], 0
	v_mov_b64_e32 v[50:51], 0
	v_mov_b64_e32 v[52:53], 0
	v_mov_b64_e32 v[54:55], 0
	v_mov_b64_e32 v[56:57], 0
	v_mov_b64_e32 v[58:59], 0
	v_mov_b64_e32 v[60:61], 0
	v_mov_b64_e32 v[62:63], 0
	v_mov_b64_e32 v[64:65], 0
	v_mov_b64_e32 v[66:67], 0
	v_mov_b64_e32 v[68:69], 0
	v_mov_b64_e32 v[70:71], 0
	v_mov_b64_e32 v[72:73], 0
	v_mov_b64_e32 v[74:75], 0
	v_mov_b64_e32 v[76:77], 0
	v_mov_b64_e32 v[78:79], 0
	v_mov_b64_e32 v[80:81], 0
	v_mov_b64_e32 v[82:83], 0
	v_mov_b64_e32 v[84:85], 0
	v_mov_b64_e32 v[86:87], 0
	v_mov_b64_e32 v[88:89], 0
	v_mov_b64_e32 v[90:91], 0
	v_mov_b64_e32 v[92:93], 0
	v_mov_b64_e32 v[94:95], 0
	v_mov_b64_e32 v[96:97], 0
	v_mov_b64_e32 v[98:99], 0
	v_mov_b64_e32 v[100:101], 0
	v_mov_b64_e32 v[102:103], 0
	v_mov_b64_e32 v[104:105], 0
	v_mov_b64_e32 v[106:107], 0
	v_mov_b64_e32 v[108:109], 0
	v_mov_b64_e32 v[110:111], 0
	v_mov_b64_e32 v[112:113], 0
	v_mov_b64_e32 v[114:115], 0
	v_mov_b64_e32 v[116:117], 0
	v_mov_b64_e32 v[118:119], 0
	v_mov_b64_e32 v[120:121], 0
	v_mov_b64_e32 v[122:123], 0
	v_mov_b64_e32 v[124:125], 0
	v_mov_b64_e32 v[126:127], 0
	v_mov_b64_e32 v[128:129], 0

; template <class Epi, class Sched, bool ALIGN_EPI, bool LAST_FUSED = false, bool PERM = false, bool CARRY = false>
; __device__ __forceinline__ void gemm_phase(LAS unsigned char* lds, const int tid, const int K, const int lda, const int ldb, const Sched& S, const Epi& E) {
;     ...
; #pragma unroll
;         for (int a = 0; a < 2; ++a)
; #pragma unroll
;             for (int b = 0; b < 2; ++b)
; #pragma unroll
;                 for (int m = 0; m < 4; ++m)
; #pragma unroll
;                     for (int n = 0; n < 2; ++n) { if constexpr (CARRY) acc[a][b][m][n] = acc[a][b][m][n] * cs_; else acc[a][b][m][n] = (f32x4){0.f, 0.f, 0.f, 0.f}; }
;         cur = nxt; cA = nA; cB = nB; ++ui;
.LBB0_511:
	s_add_u32 s4, s4, 0x80080
	s_addc_u32 s5, s5, 0
	s_add_u32 s22, s36, 0x100
	v_mov_b32_e32 v2, 0
	s_addc_u32 s23, s37, 0
	s_mov_b32 s24, -2
	v_mov_b64_e32 v[2:3], 0
	v_mov_b64_e32 v[4:5], 0
	v_mov_b64_e32 v[6:7], 0
	v_mov_b64_e32 v[8:9], 0
	v_mov_b64_e32 v[10:11], 0
	v_mov_b64_e32 v[12:13], 0
	v_mov_b64_e32 v[14:15], 0
	v_mov_b64_e32 v[16:17], 0
	v_mov_b64_e32 v[18:19], 0
	v_mov_b64_e32 v[20:21], 0
	v_mov_b64_e32 v[22:23], 0
	v_mov_b64_e32 v[24:25], 0
	v_mov_b64_e32 v[26:27], 0
	v_mov_b64_e32 v[28:29], 0
	v_mov_b64_e32 v[30:31], 0
	v_mov_b64_e32 v[32:33], 0
	v_mov_b64_e32 v[34:35], 0
	v_mov_b64_e32 v[36:37], 0
	v_mov_b64_e32 v[38:39], 0
	v_mov_b64_e32 v[40:41], 0
	v_mov_b64_e32 v[42:43], 0
	v_mov_b64_e32 v[44:45], 0
	v_mov_b64_e32 v[46:47], 0
	v_mov_b64_e32 v[48:49], 0
	v_mov_b64_e32 v[50:51], 0
	v_mov_b64_e32 v[52:53], 0
	v_mov_b64_e32 v[54:55], 0
	v_mov_b64_e32 v[56:57], 0
	v_mov_b64_e32 v[58:59], 0
	v_mov_b64_e32 v[60:61], 0
	v_mov_b64_e32 v[62:63], 0
	v_mov_b64_e32 v[64:65], 0
	v_mov_b64_e32 v[66:67], 0
	v_mov_b64_e32 v[68:69], 0
	v_mov_b64_e32 v[70:71], 0
	v_mov_b64_e32 v[72:73], 0
	v_mov_b64_e32 v[74:75], 0
	v_mov_b64_e32 v[76:77], 0
	v_mov_b64_e32 v[78:79], 0
	v_mov_b64_e32 v[80:81], 0
	v_mov_b64_e32 v[82:83], 0
	v_mov_b64_e32 v[84:85], 0
	v_mov_b64_e32 v[86:87], 0
	v_mov_b64_e32 v[88:89], 0
	v_mov_b64_e32 v[90:91], 0
	v_mov_b64_e32 v[92:93], 0
	v_mov_b64_e32 v[94:95], 0
	v_mov_b64_e32 v[96:97], 0
	v_mov_b64_e32 v[98:99], 0
	v_mov_b64_e32 v[100:101], 0
	v_mov_b64_e32 v[102:103], 0
	v_mov_b64_e32 v[104:105], 0
	v_mov_b64_e32 v[106:107], 0
	v_mov_b64_e32 v[108:109], 0
	v_mov_b64_e32 v[110:111], 0
	v_mov_b64_e32 v[112:113], 0
	v_mov_b64_e32 v[114:115], 0
	v_mov_b64_e32 v[116:117], 0
	v_mov_b64_e32 v[118:119], 0
	v_mov_b64_e32 v[120:121], 0
	v_mov_b64_e32 v[122:123], 0
	v_mov_b64_e32 v[124:125], 0
	v_mov_b64_e32 v[126:127], 0
	v_mov_b64_e32 v[128:129], 0

; template <class Epi, class Sched, bool ALIGN_EPI, bool LAST_FUSED = false, bool PERM = false, bool CARRY = false>
; __device__ __forceinline__ void gemm_phase(LAS unsigned char* lds, const int tid, const int K, const int lda, const int ldb, const Sched& S, const Epi& E) {
;     ...
;     f32x4 acc[2][2][4][2];
; #pragma unroll
;     for (int a = 0; a < 2; ++a)
; #pragma unroll
;         for (int b = 0; b < 2; ++b)
; #pragma unroll
;             for (int m = 0; m < 4; ++m)
; #pragma unroll
;                 for (int n = 0; n < 2; ++n) acc[a][b][m][n] = (f32x4){0.f, 0.f, 0.f, 0.f};
;     ...
; #pragma unroll
;         for (int a = 0; a < 2; ++a)
; #pragma unroll
;             for (int b = 0; b < 2; ++b)
; #pragma unroll
;                 for (int m = 0; m < 4; ++m)
; #pragma unroll
;                     for (int n = 0; n < 2; ++n) { if constexpr (CARRY) acc[a][b][m][n] = acc[a][b][m][n] * cs_; else acc[a][b][m][n] = (f32x4){0.f, 0.f, 0.f, 0.f}; }
;         cur = nxt; cA = nA; cB = nB; ++ui;
.LBB0_600:
	v_mov_b32_e32 v2, 0
	s_mov_b32 s15, 0
	s_mov_b64 s[38:39], -1
	s_mov_b64 s[40:41], 0
	v_mov_b64_e32 v[2:3], 0
	v_mov_b64_e32 v[4:5], 0
	v_mov_b64_e32 v[6:7], 0
	v_mov_b64_e32 v[8:9], 0
	v_mov_b64_e32 v[10:11], 0
	v_mov_b64_e32 v[12:13], 0
	v_mov_b64_e32 v[14:15], 0
	v_mov_b64_e32 v[16:17], 0
	v_mov_b64_e32 v[18:19], 0
	v_mov_b64_e32 v[20:21], 0
	v_mov_b64_e32 v[22:23], 0
	v_mov_b64_e32 v[24:25], 0
	v_mov_b64_e32 v[26:27], 0
	v_mov_b64_e32 v[28:29], 0
	v_mov_b64_e32 v[30:31], 0
	v_mov_b64_e32 v[32:33], 0
	v_mov_b64_e32 v[34:35], 0
	v_mov_b64_e32 v[36:37], 0
	v_mov_b64_e32 v[38:39], 0
	v_mov_b64_e32 v[40:41], 0
	v_mov_b64_e32 v[42:43], 0
	v_mov_b64_e32 v[44:45], 0
	v_mov_b64_e32 v[46:47], 0
	v_mov_b64_e32 v[48:49], 0
	v_mov_b64_e32 v[50:51], 0
	v_mov_b64_e32 v[52:53], 0
	v_mov_b64_e32 v[54:55], 0
	v_mov_b64_e32 v[56:57], 0
	v_mov_b64_e32 v[58:59], 0
	v_mov_b64_e32 v[60:61], 0
	v_mov_b64_e32 v[62:63], 0
	v_mov_b64_e32 v[64:65], 0
	v_mov_b64_e32 v[66:67], 0
	v_mov_b64_e32 v[68:69], 0
	v_mov_b64_e32 v[70:71], 0
	v_mov_b64_e32 v[72:73], 0
	v_mov_b64_e32 v[74:75], 0
	v_mov_b64_e32 v[76:77], 0
	v_mov_b64_e32 v[78:79], 0
	v_mov_b64_e32 v[80:81], 0
	v_mov_b64_e32 v[82:83], 0
	v_mov_b64_e32 v[84:85], 0
	v_mov_b64_e32 v[86:87], 0
	v_mov_b64_e32 v[88:89], 0
	v_mov_b64_e32 v[90:91], 0
	v_mov_b64_e32 v[92:93], 0
	v_mov_b64_e32 v[94:95], 0
	v_mov_b64_e32 v[96:97], 0
	v_mov_b64_e32 v[98:99], 0
	v_mov_b64_e32 v[100:101], 0
	v_mov_b64_e32 v[102:103], 0
	v_mov_b64_e32 v[104:105], 0
	v_mov_b64_e32 v[106:107], 0
	v_mov_b64_e32 v[108:109], 0
	v_mov_b64_e32 v[110:111], 0
	v_mov_b64_e32 v[112:113], 0
	v_mov_b64_e32 v[114:115], 0
	v_mov_b64_e32 v[116:117], 0
	v_mov_b64_e32 v[118:119], 0
	v_mov_b64_e32 v[120:121], 0
	v_mov_b64_e32 v[122:123], 0
	v_mov_b64_e32 v[124:125], 0
	v_mov_b64_e32 v[126:127], 0
	v_mov_b64_e32 v[128:129], 0

; template <class Epi, class Sched, bool ALIGN_EPI, bool LAST_FUSED = false, bool PERM = false, bool CARRY = false>
; __device__ __forceinline__ void gemm_phase(LAS unsigned char* lds, const int tid, const int K, const int lda, const int ldb, const Sched& S, const Epi& E) {
;     ...
; #pragma unroll
;         for (int a = 0; a < 2; ++a)
; #pragma unroll
;             for (int b = 0; b < 2; ++b)
; #pragma unroll
;                 for (int m = 0; m < 4; ++m)
; #pragma unroll
;                     for (int n = 0; n < 2; ++n) { if constexpr (CARRY) acc[a][b][m][n] = acc[a][b][m][n] * cs_; else acc[a][b][m][n] = (f32x4){0.f, 0.f, 0.f, 0.f}; }
;         cur = nxt; cA = nA; cB = nB; ++ui;
.LBB0_704:
	s_add_u32 s13, s30, 0x100
	v_mov_b32_e32 v2, 0
	s_addc_u32 s52, s31, 0
	s_mov_b32 s53, -2
	v_mov_b64_e32 v[2:3], 0
	v_mov_b64_e32 v[4:5], 0
	v_mov_b64_e32 v[6:7], 0
	v_mov_b64_e32 v[8:9], 0
	v_mov_b64_e32 v[10:11], 0
	v_mov_b64_e32 v[12:13], 0
	v_mov_b64_e32 v[14:15], 0
	v_mov_b64_e32 v[16:17], 0
	v_mov_b64_e32 v[18:19], 0
	v_mov_b64_e32 v[20:21], 0
	v_mov_b64_e32 v[22:23], 0
	v_mov_b64_e32 v[24:25], 0
	v_mov_b64_e32 v[26:27], 0
	v_mov_b64_e32 v[28:29], 0
	v_mov_b64_e32 v[30:31], 0
	v_mov_b64_e32 v[32:33], 0
	v_mov_b64_e32 v[34:35], 0
	v_mov_b64_e32 v[36:37], 0
	v_mov_b64_e32 v[38:39], 0
	v_mov_b64_e32 v[40:41], 0
	v_mov_b64_e32 v[42:43], 0
	v_mov_b64_e32 v[44:45], 0
	v_mov_b64_e32 v[46:47], 0
	v_mov_b64_e32 v[48:49], 0
	v_mov_b64_e32 v[50:51], 0
	v_mov_b64_e32 v[52:53], 0
	v_mov_b64_e32 v[54:55], 0
	v_mov_b64_e32 v[56:57], 0
	v_mov_b64_e32 v[58:59], 0
	v_mov_b64_e32 v[60:61], 0
	v_mov_b64_e32 v[62:63], 0
	v_mov_b64_e32 v[64:65], 0
	v_mov_b64_e32 v[66:67], 0
	v_mov_b64_e32 v[68:69], 0
	v_mov_b64_e32 v[70:71], 0
	v_mov_b64_e32 v[72:73], 0
	v_mov_b64_e32 v[74:75], 0
	v_mov_b64_e32 v[76:77], 0
	v_mov_b64_e32 v[78:79], 0
	v_mov_b64_e32 v[80:81], 0
	v_mov_b64_e32 v[82:83], 0
	v_mov_b64_e32 v[84:85], 0
	v_mov_b64_e32 v[86:87], 0
	v_mov_b64_e32 v[88:89], 0
	v_mov_b64_e32 v[90:91], 0
	v_mov_b64_e32 v[92:93], 0
	v_mov_b64_e32 v[94:95], 0
	v_mov_b64_e32 v[96:97], 0
	v_mov_b64_e32 v[98:99], 0
	v_mov_b64_e32 v[100:101], 0
	v_mov_b64_e32 v[102:103], 0
	v_mov_b64_e32 v[104:105], 0
	v_mov_b64_e32 v[106:107], 0
	v_mov_b64_e32 v[108:109], 0
	v_mov_b64_e32 v[110:111], 0
	v_mov_b64_e32 v[112:113], 0
	v_mov_b64_e32 v[114:115], 0
	v_mov_b64_e32 v[116:117], 0
	v_mov_b64_e32 v[118:119], 0
	v_mov_b64_e32 v[120:121], 0
	v_mov_b64_e32 v[122:123], 0
	v_mov_b64_e32 v[124:125], 0
	v_mov_b64_e32 v[126:127], 0
	v_mov_b64_e32 v[128:129], 0

; template <class Epi, class Sched, bool ALIGN_EPI, bool LAST_FUSED = false, bool PERM = false, bool CARRY = false>
; __device__ __forceinline__ void gemm_phase(LAS unsigned char* lds, const int tid, const int K, const int lda, const int ldb, const Sched& S, const Epi& E) {
;     ...
; #pragma unroll
;         for (int a = 0; a < 2; ++a)
; #pragma unroll
;             for (int b = 0; b < 2; ++b)
; #pragma unroll
;                 for (int m = 0; m < 4; ++m)
; #pragma unroll
;                     for (int n = 0; n < 2; ++n) { if constexpr (CARRY) acc[a][b][m][n] = acc[a][b][m][n] * cs_; else acc[a][b][m][n] = (f32x4){0.f, 0.f, 0.f, 0.f}; }
;         cur = nxt; cA = nA; cB = nB; ++ui;
.LBB0_837:
	s_add_u32 s4, s4, 0x80080
	s_addc_u32 s5, s5, 0
	s_add_u32 s22, s6, 0x100
	v_mov_b32_e32 v2, 0
	s_addc_u32 s23, s7, 0
	s_mov_b32 s28, -2
	v_mov_b64_e32 v[2:3], 0
	v_mov_b64_e32 v[4:5], 0
	v_mov_b64_e32 v[6:7], 0
	v_mov_b64_e32 v[8:9], 0
	v_mov_b64_e32 v[10:11], 0
	v_mov_b64_e32 v[12:13], 0
	v_mov_b64_e32 v[14:15], 0
	v_mov_b64_e32 v[16:17], 0
	v_mov_b64_e32 v[18:19], 0
	v_mov_b64_e32 v[20:21], 0
	v_mov_b64_e32 v[22:23], 0
	v_mov_b64_e32 v[24:25], 0
	v_mov_b64_e32 v[26:27], 0
	v_mov_b64_e32 v[28:29], 0
	v_mov_b64_e32 v[30:31], 0
	v_mov_b64_e32 v[32:33], 0
	v_mov_b64_e32 v[34:35], 0
	v_mov_b64_e32 v[36:37], 0
	v_mov_b64_e32 v[38:39], 0
	v_mov_b64_e32 v[40:41], 0
	v_mov_b64_e32 v[42:43], 0
	v_mov_b64_e32 v[44:45], 0
	v_mov_b64_e32 v[46:47], 0
	v_mov_b64_e32 v[48:49], 0
	v_mov_b64_e32 v[50:51], 0
	v_mov_b64_e32 v[52:53], 0
	v_mov_b64_e32 v[54:55], 0
	v_mov_b64_e32 v[56:57], 0
	v_mov_b64_e32 v[58:59], 0
	v_mov_b64_e32 v[60:61], 0
	v_mov_b64_e32 v[62:63], 0
	v_mov_b64_e32 v[64:65], 0
	v_mov_b64_e32 v[66:67], 0
	v_mov_b64_e32 v[68:69], 0
	v_mov_b64_e32 v[70:71], 0
	v_mov_b64_e32 v[72:73], 0
	v_mov_b64_e32 v[74:75], 0
	v_mov_b64_e32 v[76:77], 0
	v_mov_b64_e32 v[78:79], 0
	v_mov_b64_e32 v[80:81], 0
	v_mov_b64_e32 v[82:83], 0
	v_mov_b64_e32 v[84:85], 0
	v_mov_b64_e32 v[86:87], 0
	v_mov_b64_e32 v[88:89], 0
	v_mov_b64_e32 v[90:91], 0
	v_mov_b64_e32 v[92:93], 0
	v_mov_b64_e32 v[94:95], 0
	v_mov_b64_e32 v[96:97], 0
	v_mov_b64_e32 v[98:99], 0
	v_mov_b64_e32 v[100:101], 0
	v_mov_b64_e32 v[102:103], 0
	v_mov_b64_e32 v[104:105], 0
	v_mov_b64_e32 v[106:107], 0
	v_mov_b64_e32 v[108:109], 0
	v_mov_b64_e32 v[110:111], 0
	v_mov_b64_e32 v[112:113], 0
	v_mov_b64_e32 v[114:115], 0
	v_mov_b64_e32 v[116:117], 0
	v_mov_b64_e32 v[118:119], 0
	v_mov_b64_e32 v[120:121], 0
	v_mov_b64_e32 v[122:123], 0
	v_mov_b64_e32 v[124:125], 0
	v_mov_b64_e32 v[126:127], 0
	v_mov_b64_e32 v[128:129], 0

; template <class Epi, class Sched, bool ALIGN_EPI, bool LAST_FUSED = false, bool PERM = false, bool CARRY = false>
; __device__ __forceinline__ void gemm_phase(LAS unsigned char* lds, const int tid, const int K, const int lda, const int ldb, const Sched& S, const Epi& E) {
;     ...
; #pragma unroll
;         for (int a = 0; a < 2; ++a)
; #pragma unroll
;             for (int b = 0; b < 2; ++b)
; #pragma unroll
;                 for (int m = 0; m < 4; ++m)
; #pragma unroll
;                     for (int n = 0; n < 2; ++n) { if constexpr (CARRY) acc[a][b][m][n] = acc[a][b][m][n] * cs_; else acc[a][b][m][n] = (f32x4){0.f, 0.f, 0.f, 0.f}; }
;         cur = nxt; cA = nA; cB = nB; ++ui;
.LBB0_1076:
	s_add_u32 s26, s26, 0x80080
	s_addc_u32 s27, s27, 0
	s_add_u32 s5, s30, 0x100
	v_mov_b32_e32 v2, 0
	s_addc_u32 s13, s31, 0
	s_mov_b32 s15, -2
	v_mov_b64_e32 v[2:3], 0
	v_mov_b64_e32 v[4:5], 0
	v_mov_b64_e32 v[6:7], 0
	v_mov_b64_e32 v[8:9], 0
	v_mov_b64_e32 v[10:11], 0
	v_mov_b64_e32 v[12:13], 0
	v_mov_b64_e32 v[14:15], 0
	v_mov_b64_e32 v[16:17], 0
	v_mov_b64_e32 v[18:19], 0
	v_mov_b64_e32 v[20:21], 0
	v_mov_b64_e32 v[22:23], 0
	v_mov_b64_e32 v[24:25], 0
	v_mov_b64_e32 v[26:27], 0
	v_mov_b64_e32 v[28:29], 0
	v_mov_b64_e32 v[30:31], 0
	v_mov_b64_e32 v[32:33], 0
	v_mov_b64_e32 v[34:35], 0
	v_mov_b64_e32 v[36:37], 0
	v_mov_b64_e32 v[38:39], 0
	v_mov_b64_e32 v[40:41], 0
	v_mov_b64_e32 v[42:43], 0
	v_mov_b64_e32 v[44:45], 0
	v_mov_b64_e32 v[46:47], 0
	v_mov_b64_e32 v[48:49], 0
	v_mov_b64_e32 v[50:51], 0
	v_mov_b64_e32 v[52:53], 0
	v_mov_b64_e32 v[54:55], 0
	v_mov_b64_e32 v[56:57], 0
	v_mov_b64_e32 v[58:59], 0
	v_mov_b64_e32 v[60:61], 0
	v_mov_b64_e32 v[62:63], 0
	v_mov_b64_e32 v[64:65], 0
	v_mov_b64_e32 v[66:67], 0
	v_mov_b64_e32 v[68:69], 0
	v_mov_b64_e32 v[70:71], 0
	v_mov_b64_e32 v[72:73], 0
	v_mov_b64_e32 v[74:75], 0
	v_mov_b64_e32 v[76:77], 0
	v_mov_b64_e32 v[78:79], 0
	v_mov_b64_e32 v[80:81], 0
	v_mov_b64_e32 v[82:83], 0
	v_mov_b64_e32 v[84:85], 0
	v_mov_b64_e32 v[86:87], 0
	v_mov_b64_e32 v[88:89], 0
	v_mov_b64_e32 v[90:91], 0
	v_mov_b64_e32 v[92:93], 0
	v_mov_b64_e32 v[94:95], 0
	v_mov_b64_e32 v[96:97], 0
	v_mov_b64_e32 v[98:99], 0
	v_mov_b64_e32 v[100:101], 0
	v_mov_b64_e32 v[102:103], 0
	v_mov_b64_e32 v[104:105], 0
	v_mov_b64_e32 v[106:107], 0
	v_mov_b64_e32 v[108:109], 0
	v_mov_b64_e32 v[110:111], 0
	v_mov_b64_e32 v[112:113], 0
	v_mov_b64_e32 v[114:115], 0
	v_mov_b64_e32 v[116:117], 0
	v_mov_b64_e32 v[118:119], 0
	v_mov_b64_e32 v[120:121], 0
	v_mov_b64_e32 v[122:123], 0
	v_mov_b64_e32 v[124:125], 0
	v_mov_b64_e32 v[126:127], 0
	v_mov_b64_e32 v[128:129], 0

; template <class Epi, class Sched, bool ALIGN_EPI, bool LAST_FUSED = false, bool PERM = false, bool CARRY = false>
; __device__ __forceinline__ void gemm_phase(LAS unsigned char* lds, const int tid, const int K, const int lda, const int ldb, const Sched& S, const Epi& E) {
;     ...
;     f32x4 acc[2][2][4][2];
; #pragma unroll
;     for (int a = 0; a < 2; ++a)
; #pragma unroll
;         for (int b = 0; b < 2; ++b)
; #pragma unroll
;             for (int m = 0; m < 4; ++m)
; #pragma unroll
;                 for (int n = 0; n < 2; ++n) acc[a][b][m][n] = (f32x4){0.f, 0.f, 0.f, 0.f};
;     ...
; #pragma unroll
;         for (int a = 0; a < 2; ++a)
; #pragma unroll
;             for (int b = 0; b < 2; ++b)
; #pragma unroll
;                 for (int m = 0; m < 4; ++m)
; #pragma unroll
;                     for (int n = 0; n < 2; ++n) { if constexpr (CARRY) acc[a][b][m][n] = acc[a][b][m][n] * cs_; else acc[a][b][m][n] = (f32x4){0.f, 0.f, 0.f, 0.f}; }
;         cur = nxt; cA = nA; cB = nB; ++ui;
.LBB0_1366:
	v_mov_b32_e32 v2, 0
	s_mov_b32 s17, 0
	s_mov_b64 s[42:43], -1
	s_mov_b64 s[46:47], 0
	v_mov_b64_e32 v[2:3], 0
	v_mov_b64_e32 v[4:5], 0
	v_mov_b64_e32 v[6:7], 0
	v_mov_b64_e32 v[8:9], 0
	v_mov_b64_e32 v[10:11], 0
	v_mov_b64_e32 v[12:13], 0
	v_mov_b64_e32 v[14:15], 0
	v_mov_b64_e32 v[16:17], 0
	v_mov_b64_e32 v[18:19], 0
	v_mov_b64_e32 v[20:21], 0
	v_mov_b64_e32 v[22:23], 0
	v_mov_b64_e32 v[24:25], 0
	v_mov_b64_e32 v[30:31], 0
	v_mov_b64_e32 v[32:33], 0
	v_mov_b64_e32 v[42:43], 0
	v_mov_b64_e32 v[44:45], 0
	v_mov_b64_e32 v[50:51], 0
	v_mov_b64_e32 v[52:53], 0
	v_mov_b64_e32 v[62:63], 0
	v_mov_b64_e32 v[64:65], 0
	v_mov_b64_e32 v[66:67], 0
	v_mov_b64_e32 v[68:69], 0
	v_mov_b64_e32 v[70:71], 0
	v_mov_b64_e32 v[72:73], 0
	v_mov_b64_e32 v[74:75], 0
	v_mov_b64_e32 v[76:77], 0
	v_mov_b64_e32 v[78:79], 0
	v_mov_b64_e32 v[80:81], 0
	v_mov_b64_e32 v[82:83], 0
	v_mov_b64_e32 v[84:85], 0
	v_mov_b64_e32 v[86:87], 0
	v_mov_b64_e32 v[88:89], 0
	v_mov_b64_e32 v[90:91], 0
	v_mov_b64_e32 v[92:93], 0
	v_mov_b64_e32 v[94:95], 0
	v_mov_b64_e32 v[96:97], 0
	v_mov_b64_e32 v[98:99], 0
	v_mov_b64_e32 v[100:101], 0
	v_mov_b64_e32 v[102:103], 0
	v_mov_b64_e32 v[104:105], 0
	v_mov_b64_e32 v[106:107], 0
	v_mov_b64_e32 v[108:109], 0
	v_mov_b64_e32 v[110:111], 0
	v_mov_b64_e32 v[112:113], 0
	v_mov_b64_e32 v[114:115], 0
	v_mov_b64_e32 v[116:117], 0
	v_mov_b64_e32 v[118:119], 0
	v_mov_b64_e32 v[120:121], 0
	v_mov_b64_e32 v[122:123], 0
	v_mov_b64_e32 v[124:125], 0
	v_mov_b64_e32 v[126:127], 0
	v_mov_b64_e32 v[128:129], 0
	v_mov_b64_e32 v[130:131], 0
	v_mov_b64_e32 v[132:133], 0
	v_mov_b64_e32 v[134:135], 0
	v_mov_b64_e32 v[136:137], 0
	v_mov_b64_e32 v[138:139], 0
	v_mov_b64_e32 v[140:141], 0
	v_mov_b64_e32 v[142:143], 0
	v_mov_b64_e32 v[144:145], 0
	v_mov_b64_e32 v[146:147], 0
	v_mov_b64_e32 v[148:149], 0
	v_mov_b64_e32 v[150:151], 0
	v_mov_b64_e32 v[152:153], 0

; #define PG8_STAGE(bufoff, gbase, voff) do { _Pragma("unroll") for (int _i = 0; _i < 2; ++_i) \
;         __builtin_amdgcn_global_load_lds((const unsigned*)((const char*)(gbase) + (voff)[_i]), (LAS unsigned*)(lds + (bufoff) + ldsw + _i * 8192), 16, 0, 0); } while (0)
; #define PG8_WAIT_V(n) asm volatile("s_waitcnt vmcnt(" #n ")" ::: "memory")
; #define PG8_BAR __builtin_amdgcn_s_barrier()
; template <class Epi, class Sched, bool ALIGN_EPI, bool LAST_FUSED = false, bool PERM = false, bool CARRY = false>
; __device__ __forceinline__ void gemm_phase(LAS unsigned char* lds, const int tid, const int K, const int lda, const int ldb, const Sched& S, const Epi& E) {
;     ...
;     Unit cur, nxt; int ui = 0;
;     if (!S.next(0, cur)) return;
;     f32x4 acc[2][2][4][2];
; #pragma unroll
;     for (int a = 0; a < 2; ++a)
; #pragma unroll
;         for (int b = 0; b < 2; ++b)
; #pragma unroll
;             for (int m = 0; m < 4; ++m)
; #pragma unroll
;                 for (int n = 0; n < 2; ++n) acc[a][b][m][n] = (f32x4){0.f, 0.f, 0.f, 0.f};
;     bf16x8 At[4][2], B0[2][2], B1[2][2];
;     const char* cA = cur.a; const char* cB = cur.b;
;     PG8_STAGE(PG8_SB(0, 0), cB, voffB); PG8_STAGE(PG8_SB(0, 1), cB + hstepB, voffB); PG8_STAGE(PG8_SA(0, 0), cA, voffA); PG8_STAGE(PG8_SA(0, 1), cA + hstepA, voffA);
;     if (wr == 1) PG8_BAR;
;     PG8_WAIT_V(2); PG8_BAR;
;     PG8_STAGE(PG8_SB(1, 0), cB + kstep, voffB); PG8_STAGE(PG8_SA(1, 0), cA + kstep, voffA); PG8_STAGE(PG8_SB(1, 1), cB + hstepB + kstep, voffB);
;     PG8_WAIT_V(6); PG8_BAR;
.LBB0_1575:
	v_and_b32_e32 v154, 15, v238
	s_add_u32 s22, s16, 0x2ef00000
	v_bfe_u32 v155, v238, 4, 2
	v_lshlrev_b32_e32 v16, 6, v154
	v_lshlrev_b32_e32 v17, 2, v238
	s_addc_u32 s23, s17, 0
	s_and_b32 s39, s24, 3
	v_lshl_or_b32 v16, v155, 4, v16
	s_lshl_b32 s24, s31, 13
	v_and_b32_e32 v17, 32, v17
	s_add_i32 m0, s35, 0x18000
	v_lshl_add_u64 v[8:9], v[8:9], 0, s[68:69]
	v_bitop3_b32 v18, s24, v16, v17 bitop3:0xf6
	s_lshl_b32 s24, s39, 12
	s_waitcnt vmcnt(2)
	s_barrier
	global_load_lds_dwordx4 v[8:9], off
	v_lshl_add_u64 v[6:7], v[6:7], 0, s[68:69]
	s_add_i32 m0, s35, 0x1a000
	s_add_i32 s85, s35, 0x8000
	s_add_i32 s89, s35, 0xa000
	global_load_lds_dwordx4 v[6:7], off
	v_lshl_add_u64 v[2:3], v[2:3], 0, s[68:69]
	s_mov_b32 m0, s85
	s_add_u32 s36, s40, 0x80080
	global_load_lds_dwordx4 v[2:3], off
	v_lshl_add_u64 v[2:3], v[4:5], 0, s[68:69]
	s_mov_b32 m0, s89
	s_addc_u32 s37, s41, 0
	global_load_lds_dwordx4 v[2:3], off
	s_add_i32 m0, s35, 0x1c000
	v_lshl_add_u64 v[2:3], s[36:37], 0, v[0:1]
	global_load_lds_dwordx4 v[2:3], off
	v_lshl_add_u64 v[2:3], s[36:37], 0, v[122:123]
	s_add_i32 m0, s35, 0x1e000
	s_cmpk_lt_u32 s44, 0x100
	global_load_lds_dwordx4 v[2:3], off
	v_lshlrev_b32_e32 v2, 15, v10
	v_and_b32_e32 v2, 0xffff0000, v2
	v_lshl_add_u32 v2, v11, 12, v2
	v_and_b32_e32 v3, 1, v10
	v_lshl_or_b32 v2, v3, 6, v2
	v_lshl_add_u32 v2, v12, 1, v2
	v_mov_b32_e32 v3, v1
	s_mov_b64 s[44:45], 0x80080
	v_lshl_add_u64 v[124:125], v[2:3], 0, s[44:45]
	v_lshlrev_b32_e32 v2, 15, v13
	v_and_b32_e32 v2, 0xffff0000, v2
	v_lshl_add_u32 v2, v14, 12, v2
	v_and_b32_e32 v3, 1, v13
	s_waitcnt vmcnt(6)
	v_lshl_or_b32 v2, v3, 6, v2
	v_lshl_add_u32 v2, v15, 1, v2
	v_mov_b32_e32 v3, v1
	v_mov_b32_e32 v82, 0
	v_bitop3_b32 v140, s24, v16, v17 bitop3:0xf6
	s_cselect_b64 s[36:37], -1, 0
	v_lshl_add_u64 v[126:127], v[2:3], 0, s[44:45]
	s_mov_b32 s92, 0
	v_add_u32_e32 v141, 0, v18
	v_mov_b64_e32 v[2:3], 0
	v_mov_b64_e32 v[4:5], 0
	v_mov_b64_e32 v[6:7], 0
	v_mov_b64_e32 v[8:9], 0
	v_mov_b64_e32 v[10:11], 0
	v_mov_b64_e32 v[12:13], 0
	v_mov_b64_e32 v[14:15], 0
	v_mov_b64_e32 v[16:17], 0
	v_mov_b64_e32 v[18:19], 0
	v_mov_b64_e32 v[20:21], 0
	v_mov_b64_e32 v[22:23], 0
	v_mov_b64_e32 v[24:25], 0
	v_mov_b64_e32 v[26:27], 0
	v_mov_b64_e32 v[28:29], 0
	v_mov_b64_e32 v[30:31], 0
	v_mov_b64_e32 v[32:33], 0
	v_mov_b64_e32 v[34:35], 0
	v_mov_b64_e32 v[36:37], 0
	v_mov_b64_e32 v[38:39], 0
	v_mov_b64_e32 v[40:41], 0
	v_mov_b64_e32 v[42:43], 0
	v_mov_b64_e32 v[44:45], 0
	v_mov_b64_e32 v[46:47], 0
	v_mov_b64_e32 v[48:49], 0
	v_mov_b64_e32 v[50:51], 0
	v_mov_b64_e32 v[52:53], 0
	v_mov_b64_e32 v[54:55], 0
	v_mov_b64_e32 v[56:57], 0
	v_mov_b64_e32 v[58:59], 0
	v_mov_b64_e32 v[60:61], 0
	v_mov_b64_e32 v[62:63], 0
	v_mov_b64_e32 v[64:65], 0
	v_mov_b64_e32 v[66:67], 0
	v_mov_b64_e32 v[68:69], 0
	v_mov_b64_e32 v[70:71], 0
	v_mov_b64_e32 v[72:73], 0
	v_mov_b64_e32 v[74:75], 0
	v_mov_b64_e32 v[76:77], 0
	v_mov_b64_e32 v[78:79], 0
	v_mov_b64_e32 v[80:81], 0
	v_mov_b64_e32 v[82:83], 0
	v_mov_b64_e32 v[84:85], 0
	v_mov_b64_e32 v[86:87], 0
	v_mov_b64_e32 v[88:89], 0
	v_mov_b64_e32 v[90:91], 0
	v_mov_b64_e32 v[92:93], 0
	v_mov_b64_e32 v[94:95], 0
	v_mov_b64_e32 v[96:97], 0
	v_mov_b64_e32 v[98:99], 0
	v_mov_b64_e32 v[100:101], 0
	v_mov_b64_e32 v[102:103], 0
	v_mov_b64_e32 v[104:105], 0
	v_mov_b64_e32 v[106:107], 0
	v_mov_b64_e32 v[108:109], 0
	v_mov_b64_e32 v[110:111], 0
	v_mov_b64_e32 v[112:113], 0
	v_mov_b64_e32 v[114:115], 0
	v_mov_b64_e32 v[116:117], 0
	v_mov_b64_e32 v[118:119], 0
	v_mov_b64_e32 v[120:121], 0
	v_mov_b64_e32 v[130:131], 0
	v_mov_b64_e32 v[132:133], 0
	v_mov_b64_e32 v[134:135], 0
	v_mov_b64_e32 v[136:137], 0
	s_barrier
	s_branch .LBB0_1578

; #define PG8_BAR __builtin_amdgcn_s_barrier()
; template <class Epi, class Sched, bool ALIGN_EPI, bool LAST_FUSED = false, bool PERM = false, bool CARRY = false>
; __device__ __forceinline__ void gemm_phase(LAS unsigned char* lds, const int tid, const int K, const int lda, const int ldb, const Sched& S, const Epi& E) {
;     ...
; #pragma unroll
;         for (int a = 0; a < 2; ++a)
; #pragma unroll
;             for (int b = 0; b < 2; ++b)
; #pragma unroll
;                 for (int m = 0; m < 4; ++m)
; #pragma unroll
;                     for (int n = 0; n < 2; ++n) { if constexpr (CARRY) acc[a][b][m][n] = acc[a][b][m][n] * cs_; else acc[a][b][m][n] = (f32x4){0.f, 0.f, 0.f, 0.f}; }
;         cur = nxt; cA = nA; cB = nB; ++ui;
;         if constexpr (ALIGN_EPI) { if (wr == 1) PG8_BAR; }
.LBB0_1591:
	s_nop 0
	v_mov_b32_e32 v82, 0
	s_mov_b32 s2, s44
	s_mov_b32 s3, s45
	s_mov_b32 s38, s90
	s_mov_b32 s30, s54
	s_mov_b64 s[40:41], s[58:59]
	s_mov_b64 s[42:43], s[50:51]
	v_mov_b64_e32 v[2:3], 0
	v_mov_b64_e32 v[4:5], 0
	v_mov_b64_e32 v[6:7], 0
	v_mov_b64_e32 v[8:9], 0
	v_mov_b64_e32 v[10:11], 0
	v_mov_b64_e32 v[12:13], 0
	v_mov_b64_e32 v[14:15], 0
	v_mov_b64_e32 v[16:17], 0
	v_mov_b64_e32 v[18:19], 0
	v_mov_b64_e32 v[20:21], 0
	v_mov_b64_e32 v[22:23], 0
	v_mov_b64_e32 v[24:25], 0
	v_mov_b64_e32 v[26:27], 0
	v_mov_b64_e32 v[28:29], 0
	v_mov_b64_e32 v[30:31], 0
	v_mov_b64_e32 v[32:33], 0
	v_mov_b64_e32 v[34:35], 0
	v_mov_b64_e32 v[36:37], 0
	v_mov_b64_e32 v[38:39], 0
	v_mov_b64_e32 v[40:41], 0
	v_mov_b64_e32 v[42:43], 0
	v_mov_b64_e32 v[44:45], 0
	v_mov_b64_e32 v[46:47], 0
	v_mov_b64_e32 v[48:49], 0
	v_mov_b64_e32 v[50:51], 0
	v_mov_b64_e32 v[52:53], 0
	v_mov_b64_e32 v[54:55], 0
	v_mov_b64_e32 v[56:57], 0
	v_mov_b64_e32 v[58:59], 0
	v_mov_b64_e32 v[60:61], 0
	v_mov_b64_e32 v[62:63], 0
	v_mov_b64_e32 v[64:65], 0
	v_mov_b64_e32 v[66:67], 0
	v_mov_b64_e32 v[68:69], 0
	v_mov_b64_e32 v[70:71], 0
	v_mov_b64_e32 v[72:73], 0
	v_mov_b64_e32 v[74:75], 0
	v_mov_b64_e32 v[76:77], 0
	v_mov_b64_e32 v[78:79], 0
	v_mov_b64_e32 v[80:81], 0
	v_mov_b64_e32 v[82:83], 0
	v_mov_b64_e32 v[84:85], 0
	v_mov_b64_e32 v[86:87], 0
	v_mov_b64_e32 v[88:89], 0
	v_mov_b64_e32 v[90:91], 0
	v_mov_b64_e32 v[92:93], 0
	v_mov_b64_e32 v[94:95], 0
	v_mov_b64_e32 v[96:97], 0
	v_mov_b64_e32 v[98:99], 0
	v_mov_b64_e32 v[100:101], 0
	v_mov_b64_e32 v[102:103], 0
	v_mov_b64_e32 v[104:105], 0
	v_mov_b64_e32 v[106:107], 0
	v_mov_b64_e32 v[108:109], 0
	v_mov_b64_e32 v[110:111], 0
	v_mov_b64_e32 v[112:113], 0
	v_mov_b64_e32 v[114:115], 0
	v_mov_b64_e32 v[116:117], 0
	v_mov_b64_e32 v[118:119], 0
	v_mov_b64_e32 v[120:121], 0
	v_mov_b64_e32 v[130:131], 0
	v_mov_b64_e32 v[132:133], 0
	v_mov_b64_e32 v[134:135], 0
	v_mov_b64_e32 v[136:137], 0
	s_andn2_b64 vcc, exec, s[62:63]
	s_cbranch_vccnz .LBB0_1577

; #define PG8_STAGE(bufoff, gbase, voff) do { _Pragma("unroll") for (int _i = 0; _i < 2; ++_i) \
;         __builtin_amdgcn_global_load_lds((const unsigned*)((const char*)(gbase) + (voff)[_i]), (LAS unsigned*)(lds + (bufoff) + ldsw + _i * 8192), 16, 0, 0); } while (0)
; #define PG8_WAIT_V(n) asm volatile("s_waitcnt vmcnt(" #n ")" ::: "memory")
; #define PG8_BAR __builtin_amdgcn_s_barrier()
; template <class Epi, class Sched, bool ALIGN_EPI, bool LAST_FUSED = false, bool PERM = false, bool CARRY = false>
; __device__ __forceinline__ void gemm_phase(LAS unsigned char* lds, const int tid, const int K, const int lda, const int ldb, const Sched& S, const Epi& E) {
;     ...
;     Unit cur, nxt; int ui = 0;
;     if (!S.next(0, cur)) return;
;     f32x4 acc[2][2][4][2];
; #pragma unroll
;     for (int a = 0; a < 2; ++a)
; #pragma unroll
;         for (int b = 0; b < 2; ++b)
; #pragma unroll
;             for (int m = 0; m < 4; ++m)
; #pragma unroll
;                 for (int n = 0; n < 2; ++n) acc[a][b][m][n] = (f32x4){0.f, 0.f, 0.f, 0.f};
;     bf16x8 At[4][2], B0[2][2], B1[2][2];
;     const char* cA = cur.a; const char* cB = cur.b;
;     PG8_STAGE(PG8_SB(0, 0), cB, voffB); PG8_STAGE(PG8_SB(0, 1), cB + hstepB, voffB); PG8_STAGE(PG8_SA(0, 0), cA, voffA); PG8_STAGE(PG8_SA(0, 1), cA + hstepA, voffA);
;     if (wr == 1) PG8_BAR;
;     PG8_WAIT_V(2); PG8_BAR;
;     PG8_STAGE(PG8_SB(1, 0), cB + kstep, voffB); PG8_STAGE(PG8_SA(1, 0), cA + kstep, voffA); PG8_STAGE(PG8_SB(1, 1), cB + hstepB + kstep, voffB);
;     PG8_WAIT_V(6); PG8_BAR;
.LBB0_1652:
	v_and_b32_e32 v154, 15, v238
	s_add_u32 s22, s16, 0x2ef00000
	v_bfe_u32 v155, v238, 4, 2
	v_lshlrev_b32_e32 v16, 6, v154
	v_lshlrev_b32_e32 v17, 2, v238
	s_addc_u32 s23, s17, 0
	s_and_b32 s31, s24, 3
	v_lshl_or_b32 v16, v155, 4, v16
	s_lshl_b32 s24, s5, 13
	v_and_b32_e32 v17, 32, v17
	s_add_i32 m0, s35, 0x18000
	v_lshl_add_u64 v[8:9], v[8:9], 0, s[68:69]
	v_bitop3_b32 v18, s24, v16, v17 bitop3:0xf6
	s_lshl_b32 s24, s31, 12
	s_waitcnt vmcnt(2)
	s_barrier
	global_load_lds_dwordx4 v[8:9], off
	v_lshl_add_u64 v[6:7], v[6:7], 0, s[68:69]
	s_add_i32 m0, s35, 0x1a000
	s_add_i32 s77, s35, 0x8000
	s_add_i32 s79, s35, 0xa000
	global_load_lds_dwordx4 v[6:7], off
	v_lshl_add_u64 v[2:3], v[2:3], 0, s[68:69]
	s_mov_b32 m0, s77
	s_add_u32 s36, s40, 0x100080
	global_load_lds_dwordx4 v[2:3], off
	v_lshl_add_u64 v[2:3], v[4:5], 0, s[68:69]
	s_mov_b32 m0, s79
	s_addc_u32 s37, s41, 0
	global_load_lds_dwordx4 v[2:3], off
	s_add_i32 m0, s35, 0x1c000
	v_lshl_add_u64 v[2:3], s[36:37], 0, v[0:1]
	global_load_lds_dwordx4 v[2:3], off
	v_lshl_add_u64 v[2:3], s[36:37], 0, v[122:123]
	s_add_i32 m0, s35, 0x1e000
	s_cmpk_lt_u32 s44, 0x100
	global_load_lds_dwordx4 v[2:3], off
	v_lshlrev_b32_e32 v2, 16, v10
	v_and_b32_e32 v2, 0xfffe0000, v2
	v_lshl_add_u32 v2, v11, 13, v2
	v_and_b32_e32 v3, 1, v10
	v_lshl_or_b32 v2, v3, 6, v2
	v_lshl_add_u32 v2, v12, 1, v2
	v_mov_b32_e32 v3, v1
	s_mov_b64 s[44:45], 0x100080
	v_lshl_add_u64 v[124:125], v[2:3], 0, s[44:45]
	v_lshlrev_b32_e32 v2, 16, v13
	v_and_b32_e32 v2, 0xfffe0000, v2
	v_lshl_add_u32 v2, v14, 13, v2
	v_and_b32_e32 v3, 1, v13
	s_waitcnt vmcnt(6)
	v_lshl_or_b32 v2, v3, 6, v2
	v_lshl_add_u32 v2, v15, 1, v2
	v_mov_b32_e32 v3, v1
	v_mov_b32_e32 v82, 0
	v_bitop3_b32 v140, s24, v16, v17 bitop3:0xf6
	s_cselect_b64 s[36:37], -1, 0
	v_lshl_add_u64 v[126:127], v[2:3], 0, s[44:45]
	s_mov_b32 s81, 0
	v_add_u32_e32 v141, 0, v18
	v_mov_b64_e32 v[2:3], 0
	v_mov_b64_e32 v[4:5], 0
	v_mov_b64_e32 v[6:7], 0
	v_mov_b64_e32 v[8:9], 0
	v_mov_b64_e32 v[10:11], 0
	v_mov_b64_e32 v[12:13], 0
	v_mov_b64_e32 v[14:15], 0
	v_mov_b64_e32 v[16:17], 0
	v_mov_b64_e32 v[18:19], 0
	v_mov_b64_e32 v[20:21], 0
	v_mov_b64_e32 v[22:23], 0
	v_mov_b64_e32 v[24:25], 0
	v_mov_b64_e32 v[26:27], 0
	v_mov_b64_e32 v[28:29], 0
	v_mov_b64_e32 v[30:31], 0
	v_mov_b64_e32 v[32:33], 0
	v_mov_b64_e32 v[34:35], 0
	v_mov_b64_e32 v[36:37], 0
	v_mov_b64_e32 v[38:39], 0
	v_mov_b64_e32 v[40:41], 0
	v_mov_b64_e32 v[42:43], 0
	v_mov_b64_e32 v[44:45], 0
	v_mov_b64_e32 v[46:47], 0
	v_mov_b64_e32 v[48:49], 0
	v_mov_b64_e32 v[50:51], 0
	v_mov_b64_e32 v[52:53], 0
	v_mov_b64_e32 v[54:55], 0
	v_mov_b64_e32 v[56:57], 0
	v_mov_b64_e32 v[58:59], 0
	v_mov_b64_e32 v[60:61], 0
	v_mov_b64_e32 v[62:63], 0
	v_mov_b64_e32 v[64:65], 0
	v_mov_b64_e32 v[66:67], 0
	v_mov_b64_e32 v[68:69], 0
	v_mov_b64_e32 v[70:71], 0
	v_mov_b64_e32 v[72:73], 0
	v_mov_b64_e32 v[74:75], 0
	v_mov_b64_e32 v[76:77], 0
	v_mov_b64_e32 v[78:79], 0
	v_mov_b64_e32 v[80:81], 0
	v_mov_b64_e32 v[82:83], 0
	v_mov_b64_e32 v[84:85], 0
	v_mov_b64_e32 v[86:87], 0
	v_mov_b64_e32 v[88:89], 0
	v_mov_b64_e32 v[90:91], 0
	v_mov_b64_e32 v[92:93], 0
	v_mov_b64_e32 v[94:95], 0
	v_mov_b64_e32 v[96:97], 0
	v_mov_b64_e32 v[98:99], 0
	v_mov_b64_e32 v[100:101], 0
	v_mov_b64_e32 v[102:103], 0
	v_mov_b64_e32 v[104:105], 0
	v_mov_b64_e32 v[106:107], 0
	v_mov_b64_e32 v[108:109], 0
	v_mov_b64_e32 v[110:111], 0
	v_mov_b64_e32 v[112:113], 0
	v_mov_b64_e32 v[114:115], 0
	v_mov_b64_e32 v[116:117], 0
	v_mov_b64_e32 v[118:119], 0
	v_mov_b64_e32 v[120:121], 0
	v_mov_b64_e32 v[130:131], 0
	v_mov_b64_e32 v[132:133], 0
	v_mov_b64_e32 v[134:135], 0
	v_mov_b64_e32 v[136:137], 0
	s_barrier
	s_branch .LBB0_1655

; #define PG8_BAR __builtin_amdgcn_s_barrier()
; template <class Epi, class Sched, bool ALIGN_EPI, bool LAST_FUSED = false, bool PERM = false, bool CARRY = false>
; __device__ __forceinline__ void gemm_phase(LAS unsigned char* lds, const int tid, const int K, const int lda, const int ldb, const Sched& S, const Epi& E) {
;     ...
; #pragma unroll
;         for (int a = 0; a < 2; ++a)
; #pragma unroll
;             for (int b = 0; b < 2; ++b)
; #pragma unroll
;                 for (int m = 0; m < 4; ++m)
; #pragma unroll
;                     for (int n = 0; n < 2; ++n) { if constexpr (CARRY) acc[a][b][m][n] = acc[a][b][m][n] * cs_; else acc[a][b][m][n] = (f32x4){0.f, 0.f, 0.f, 0.f}; }
;         cur = nxt; cA = nA; cB = nB; ++ui;
;         if constexpr (ALIGN_EPI) { if (wr == 1) PG8_BAR; }
.LBB0_1668:
	s_nop 0
	v_mov_b32_e32 v82, 0
	s_mov_b32 s2, s45
	s_mov_b32 s3, s55
	s_mov_b32 s4, s44
	s_mov_b32 s30, s54
	s_mov_b64 s[40:41], s[58:59]
	s_mov_b64 s[38:39], s[50:51]
	v_mov_b64_e32 v[2:3], 0
	v_mov_b64_e32 v[4:5], 0
	v_mov_b64_e32 v[6:7], 0
	v_mov_b64_e32 v[8:9], 0
	v_mov_b64_e32 v[10:11], 0
	v_mov_b64_e32 v[12:13], 0
	v_mov_b64_e32 v[14:15], 0
	v_mov_b64_e32 v[16:17], 0
	v_mov_b64_e32 v[18:19], 0
	v_mov_b64_e32 v[20:21], 0
	v_mov_b64_e32 v[22:23], 0
	v_mov_b64_e32 v[24:25], 0
	v_mov_b64_e32 v[26:27], 0
	v_mov_b64_e32 v[28:29], 0
	v_mov_b64_e32 v[30:31], 0
	v_mov_b64_e32 v[32:33], 0
	v_mov_b64_e32 v[34:35], 0
	v_mov_b64_e32 v[36:37], 0
	v_mov_b64_e32 v[38:39], 0
	v_mov_b64_e32 v[40:41], 0
	v_mov_b64_e32 v[42:43], 0
	v_mov_b64_e32 v[44:45], 0
	v_mov_b64_e32 v[46:47], 0
	v_mov_b64_e32 v[48:49], 0
	v_mov_b64_e32 v[50:51], 0
	v_mov_b64_e32 v[52:53], 0
	v_mov_b64_e32 v[54:55], 0
	v_mov_b64_e32 v[56:57], 0
	v_mov_b64_e32 v[58:59], 0
	v_mov_b64_e32 v[60:61], 0
	v_mov_b64_e32 v[62:63], 0
	v_mov_b64_e32 v[64:65], 0
	v_mov_b64_e32 v[66:67], 0
	v_mov_b64_e32 v[68:69], 0
	v_mov_b64_e32 v[70:71], 0
	v_mov_b64_e32 v[72:73], 0
	v_mov_b64_e32 v[74:75], 0
	v_mov_b64_e32 v[76:77], 0
	v_mov_b64_e32 v[78:79], 0
	v_mov_b64_e32 v[80:81], 0
	v_mov_b64_e32 v[82:83], 0
	v_mov_b64_e32 v[84:85], 0
	v_mov_b64_e32 v[86:87], 0
	v_mov_b64_e32 v[88:89], 0
	v_mov_b64_e32 v[90:91], 0
	v_mov_b64_e32 v[92:93], 0
	v_mov_b64_e32 v[94:95], 0
	v_mov_b64_e32 v[96:97], 0
	v_mov_b64_e32 v[98:99], 0
	v_mov_b64_e32 v[100:101], 0
	v_mov_b64_e32 v[102:103], 0
	v_mov_b64_e32 v[104:105], 0
	v_mov_b64_e32 v[106:107], 0
	v_mov_b64_e32 v[108:109], 0
	v_mov_b64_e32 v[110:111], 0
	v_mov_b64_e32 v[112:113], 0
	v_mov_b64_e32 v[114:115], 0
	v_mov_b64_e32 v[116:117], 0
	v_mov_b64_e32 v[118:119], 0
	v_mov_b64_e32 v[120:121], 0
	v_mov_b64_e32 v[130:131], 0
	v_mov_b64_e32 v[132:133], 0
	v_mov_b64_e32 v[134:135], 0
	v_mov_b64_e32 v[136:137], 0
	s_andn2_b64 vcc, exec, s[62:63]
	s_cbranch_vccnz .LBB0_1654

; template <class Epi, class Sched, bool ALIGN_EPI, bool LAST_FUSED = false, bool PERM = false, bool CARRY = false>
; __device__ __forceinline__ void gemm_phase(LAS unsigned char* lds, const int tid, const int K, const int lda, const int ldb, const Sched& S, const Epi& E) {
;     ...
; #pragma unroll
;         for (int a = 0; a < 2; ++a)
; #pragma unroll
;             for (int b = 0; b < 2; ++b)
; #pragma unroll
;                 for (int m = 0; m < 4; ++m)
; #pragma unroll
;                     for (int n = 0; n < 2; ++n) { if constexpr (CARRY) acc[a][b][m][n] = acc[a][b][m][n] * cs_; else acc[a][b][m][n] = (f32x4){0.f, 0.f, 0.f, 0.f}; }
;         cur = nxt; cA = nA; cB = nB; ++ui;
.LBB0_1762:
	s_add_u32 s48, s48, 0x80080
	s_addc_u32 s49, s49, 0
	s_add_u32 s27, s54, 0x100
	v_mov_b32_e32 v2, 0
	s_addc_u32 s39, s55, 0
	s_mov_b32 s41, -2
	v_mov_b64_e32 v[2:3], 0
	v_mov_b64_e32 v[4:5], 0
	v_mov_b64_e32 v[6:7], 0
	v_mov_b64_e32 v[8:9], 0
	v_mov_b64_e32 v[10:11], 0
	v_mov_b64_e32 v[12:13], 0
	v_mov_b64_e32 v[14:15], 0
	v_mov_b64_e32 v[16:17], 0
	v_mov_b64_e32 v[18:19], 0
	v_mov_b64_e32 v[20:21], 0
	v_mov_b64_e32 v[22:23], 0
	v_mov_b64_e32 v[24:25], 0
	v_mov_b64_e32 v[26:27], 0
	v_mov_b64_e32 v[28:29], 0
	v_mov_b64_e32 v[30:31], 0
	v_mov_b64_e32 v[32:33], 0
	v_mov_b64_e32 v[34:35], 0
	v_mov_b64_e32 v[36:37], 0
	v_mov_b64_e32 v[38:39], 0
	v_mov_b64_e32 v[40:41], 0
	v_mov_b64_e32 v[42:43], 0
	v_mov_b64_e32 v[44:45], 0
	v_mov_b64_e32 v[46:47], 0
	v_mov_b64_e32 v[48:49], 0
	v_mov_b64_e32 v[50:51], 0
	v_mov_b64_e32 v[52:53], 0
	v_mov_b64_e32 v[54:55], 0
	v_mov_b64_e32 v[56:57], 0
	v_mov_b64_e32 v[58:59], 0
	v_mov_b64_e32 v[60:61], 0
	v_mov_b64_e32 v[62:63], 0
	v_mov_b64_e32 v[64:65], 0
	v_mov_b64_e32 v[66:67], 0
	v_mov_b64_e32 v[68:69], 0
	v_mov_b64_e32 v[70:71], 0
	v_mov_b64_e32 v[72:73], 0
	v_mov_b64_e32 v[74:75], 0
	v_mov_b64_e32 v[76:77], 0
	v_mov_b64_e32 v[78:79], 0
	v_mov_b64_e32 v[80:81], 0
	v_mov_b64_e32 v[82:83], 0
	v_mov_b64_e32 v[84:85], 0
	v_mov_b64_e32 v[86:87], 0
	v_mov_b64_e32 v[88:89], 0
	v_mov_b64_e32 v[90:91], 0
	v_mov_b64_e32 v[92:93], 0
	v_mov_b64_e32 v[94:95], 0
	v_mov_b64_e32 v[96:97], 0
	v_mov_b64_e32 v[98:99], 0
	v_mov_b64_e32 v[100:101], 0
	v_mov_b64_e32 v[102:103], 0
	v_mov_b64_e32 v[104:105], 0
	v_mov_b64_e32 v[106:107], 0
	v_mov_b64_e32 v[108:109], 0
	v_mov_b64_e32 v[110:111], 0
	v_mov_b64_e32 v[112:113], 0
	v_mov_b64_e32 v[114:115], 0
	v_mov_b64_e32 v[116:117], 0
	v_mov_b64_e32 v[118:119], 0
	v_mov_b64_e32 v[120:121], 0
	v_mov_b64_e32 v[122:123], 0
	v_mov_b64_e32 v[124:125], 0
	v_mov_b64_e32 v[126:127], 0
	v_mov_b64_e32 v[128:129], 0

; #define PG8_STAGE(bufoff, gbase, voff) do { _Pragma("unroll") for (int _i = 0; _i < 2; ++_i) \
;         __builtin_amdgcn_global_load_lds((const unsigned*)((const char*)(gbase) + (voff)[_i]), (LAS unsigned*)(lds + (bufoff) + ldsw + _i * 8192), 16, 0, 0); } while (0)
; #define PG8_WAIT_V(n) asm volatile("s_waitcnt vmcnt(" #n ")" ::: "memory")
; #define PG8_BAR __builtin_amdgcn_s_barrier()
; template <class Epi, class Sched, bool ALIGN_EPI, bool LAST_FUSED = false, bool PERM = false, bool CARRY = false>
; __device__ __forceinline__ void gemm_phase(LAS unsigned char* lds, const int tid, const int K, const int lda, const int ldb, const Sched& S, const Epi& E) {
;     ...
;     Unit cur, nxt; int ui = 0;
;     if (!S.next(0, cur)) return;
;     f32x4 acc[2][2][4][2];
; #pragma unroll
;     for (int a = 0; a < 2; ++a)
; #pragma unroll
;         for (int b = 0; b < 2; ++b)
; #pragma unroll
;             for (int m = 0; m < 4; ++m)
; #pragma unroll
;                 for (int n = 0; n < 2; ++n) acc[a][b][m][n] = (f32x4){0.f, 0.f, 0.f, 0.f};
;     bf16x8 At[4][2], B0[2][2], B1[2][2];
;     const char* cA = cur.a; const char* cB = cur.b;
;     PG8_STAGE(PG8_SB(0, 0), cB, voffB); PG8_STAGE(PG8_SB(0, 1), cB + hstepB, voffB); PG8_STAGE(PG8_SA(0, 0), cA, voffA); PG8_STAGE(PG8_SA(0, 1), cA + hstepA, voffA);
;     if (wr == 1) PG8_BAR;
;     PG8_WAIT_V(2); PG8_BAR;
;     PG8_STAGE(PG8_SB(1, 0), cB + kstep, voffB); PG8_STAGE(PG8_SA(1, 0), cA + kstep, voffA); PG8_STAGE(PG8_SB(1, 1), cB + hstepB + kstep, voffB);
;     PG8_WAIT_V(6); PG8_BAR;
.LBB0_1844:
	v_and_b32_e32 v156, 15, v10
	s_add_u32 s23, s8, 0x2ef00000
	v_bfe_u32 v157, v10, 4, 2
	v_lshlrev_b32_e32 v17, 6, v156
	v_lshlrev_b32_e32 v10, 2, v10
	s_addc_u32 s85, s9, 0
	s_and_b32 s59, s24, 3
	v_lshl_or_b32 v17, v157, 4, v17
	s_lshl_b32 s16, s5, 13
	v_and_b32_e32 v10, 32, v10
	s_add_i32 m0, s28, 0x18000
	v_lshl_add_u64 v[8:9], v[8:9], 0, s[68:69]
	v_bitop3_b32 v18, s16, v17, v10 bitop3:0xf6
	s_lshl_b32 s16, s59, 12
	s_waitcnt vmcnt(2)
	s_barrier
	global_load_lds_dwordx4 v[8:9], off
	v_lshl_add_u64 v[6:7], v[6:7], 0, s[68:69]
	s_add_i32 m0, s28, 0x1a000
	s_add_i32 s96, s28, 0x8000
	s_add_i32 s97, s28, 0xa000
	global_load_lds_dwordx4 v[6:7], off
	v_lshl_add_u64 v[2:3], v[2:3], 0, s[68:69]
	s_mov_b32 m0, s96
	s_add_u32 s40, s50, 0x200080
	global_load_lds_dwordx4 v[2:3], off
	v_lshl_add_u64 v[2:3], v[4:5], 0, s[68:69]
	s_mov_b32 m0, s97
	s_addc_u32 s41, s51, 0
	global_load_lds_dwordx4 v[2:3], off
	s_add_i32 m0, s28, 0x1c000
	v_lshl_add_u64 v[2:3], s[40:41], 0, v[0:1]
	global_load_lds_dwordx4 v[2:3], off
	v_lshl_add_u64 v[2:3], s[40:41], 0, v[122:123]
	s_add_i32 m0, s28, 0x1e000
	v_bitop3_b32 v140, s16, v17, v10 bitop3:0xf6
	global_load_lds_dwordx4 v[2:3], off
	v_lshlrev_b32_e32 v2, 17, v11
	v_and_b32_e32 v2, 0xfffc0000, v2
	v_lshl_add_u32 v2, v12, 14, v2
	v_and_b32_e32 v3, 1, v11
	v_lshl_or_b32 v2, v3, 6, v2
	v_lshl_add_u32 v2, v13, 1, v2
	v_mov_b32_e32 v3, v1
	s_mov_b64 s[16:17], 0x200080
	v_lshl_add_u64 v[124:125], v[2:3], 0, s[16:17]
	v_lshlrev_b32_e32 v2, 17, v14
	v_and_b32_e32 v2, 0xfffc0000, v2
	v_lshl_add_u32 v2, v15, 14, v2
	v_and_b32_e32 v3, 1, v14
	v_lshl_or_b32 v2, v3, 6, v2
	s_waitcnt vmcnt(6)
	v_lshl_add_u32 v2, v16, 1, v2
	v_mov_b32_e32 v3, v1
	s_cmpk_lt_u32 s26, 0x100
	v_lshl_add_u64 v[126:127], v[2:3], 0, s[16:17]
	v_mov_b32_e32 v2, 0
	s_cselect_b64 s[40:41], -1, 0
	s_mov_b32 s27, 0
	v_add_u32_e32 v141, 0, v18
	v_mov_b64_e32 v[2:3], 0
	v_mov_b64_e32 v[4:5], 0
	v_mov_b64_e32 v[6:7], 0
	v_mov_b64_e32 v[8:9], 0
	v_mov_b64_e32 v[10:11], 0
	v_mov_b64_e32 v[12:13], 0
	v_mov_b64_e32 v[14:15], 0
	v_mov_b64_e32 v[16:17], 0
	v_mov_b64_e32 v[18:19], 0
	v_mov_b64_e32 v[20:21], 0
	v_mov_b64_e32 v[22:23], 0
	v_mov_b64_e32 v[24:25], 0
	v_mov_b64_e32 v[26:27], 0
	v_mov_b64_e32 v[28:29], 0
	v_mov_b64_e32 v[30:31], 0
	v_mov_b64_e32 v[32:33], 0
	v_mov_b64_e32 v[34:35], 0
	v_mov_b64_e32 v[36:37], 0
	v_mov_b64_e32 v[38:39], 0
	v_mov_b64_e32 v[40:41], 0
	v_mov_b64_e32 v[42:43], 0
	v_mov_b64_e32 v[44:45], 0
	v_mov_b64_e32 v[46:47], 0
	v_mov_b64_e32 v[48:49], 0
	v_mov_b64_e32 v[50:51], 0
	v_mov_b64_e32 v[52:53], 0
	v_mov_b64_e32 v[54:55], 0
	v_mov_b64_e32 v[56:57], 0
	v_mov_b64_e32 v[58:59], 0
	v_mov_b64_e32 v[60:61], 0
	v_mov_b64_e32 v[62:63], 0
	v_mov_b64_e32 v[64:65], 0
	v_mov_b64_e32 v[66:67], 0
	v_mov_b64_e32 v[68:69], 0
	v_mov_b64_e32 v[70:71], 0
	v_mov_b64_e32 v[72:73], 0
	v_mov_b64_e32 v[74:75], 0
	v_mov_b64_e32 v[76:77], 0
	v_mov_b64_e32 v[78:79], 0
	v_mov_b64_e32 v[80:81], 0
	v_mov_b64_e32 v[82:83], 0
	v_mov_b64_e32 v[84:85], 0
	v_mov_b64_e32 v[86:87], 0
	v_mov_b64_e32 v[88:89], 0
	v_mov_b64_e32 v[90:91], 0
	v_mov_b64_e32 v[92:93], 0
	v_mov_b64_e32 v[94:95], 0
	v_mov_b64_e32 v[96:97], 0
	v_mov_b64_e32 v[98:99], 0
	v_mov_b64_e32 v[100:101], 0
	v_mov_b64_e32 v[102:103], 0
	v_mov_b64_e32 v[104:105], 0
	v_mov_b64_e32 v[106:107], 0
	v_mov_b64_e32 v[108:109], 0
	v_mov_b64_e32 v[110:111], 0
	v_mov_b64_e32 v[112:113], 0
	v_mov_b64_e32 v[114:115], 0
	v_mov_b64_e32 v[116:117], 0
	v_mov_b64_e32 v[118:119], 0
	v_mov_b64_e32 v[120:121], 0
	v_mov_b64_e32 v[130:131], 0
	v_mov_b64_e32 v[132:133], 0
	v_mov_b64_e32 v[134:135], 0
	v_mov_b64_e32 v[136:137], 0
	s_barrier
	s_branch .LBB0_1847

; #define PG8_BAR __builtin_amdgcn_s_barrier()
; template <class Epi, class Sched, bool ALIGN_EPI, bool LAST_FUSED = false, bool PERM = false, bool CARRY = false>
; __device__ __forceinline__ void gemm_phase(LAS unsigned char* lds, const int tid, const int K, const int lda, const int ldb, const Sched& S, const Epi& E) {
;     ...
; #pragma unroll
;         for (int a = 0; a < 2; ++a)
; #pragma unroll
;             for (int b = 0; b < 2; ++b)
; #pragma unroll
;                 for (int m = 0; m < 4; ++m)
; #pragma unroll
;                     for (int n = 0; n < 2; ++n) { if constexpr (CARRY) acc[a][b][m][n] = acc[a][b][m][n] * cs_; else acc[a][b][m][n] = (f32x4){0.f, 0.f, 0.f, 0.f}; }
;         cur = nxt; cA = nA; cB = nB; ++ui;
;         if constexpr (ALIGN_EPI) { if (wr == 1) PG8_BAR; }
.LBB0_1860:
	s_nop 0
	v_mov_b32_e32 v2, 0
	s_mov_b32 s86, s43
	s_mov_b32 s87, s45
	s_mov_b32 s4, s44
	s_mov_b32 s58, s42
	s_mov_b64 s[50:51], s[62:63]
	s_mov_b64 s[66:67], s[54:55]
	v_mov_b64_e32 v[2:3], 0
	v_mov_b64_e32 v[4:5], 0
	v_mov_b64_e32 v[6:7], 0
	v_mov_b64_e32 v[8:9], 0
	v_mov_b64_e32 v[10:11], 0
	v_mov_b64_e32 v[12:13], 0
	v_mov_b64_e32 v[14:15], 0
	v_mov_b64_e32 v[16:17], 0
	v_mov_b64_e32 v[18:19], 0
	v_mov_b64_e32 v[20:21], 0
	v_mov_b64_e32 v[22:23], 0
	v_mov_b64_e32 v[24:25], 0
	v_mov_b64_e32 v[26:27], 0
	v_mov_b64_e32 v[28:29], 0
	v_mov_b64_e32 v[30:31], 0
	v_mov_b64_e32 v[32:33], 0
	v_mov_b64_e32 v[34:35], 0
	v_mov_b64_e32 v[36:37], 0
	v_mov_b64_e32 v[38:39], 0
	v_mov_b64_e32 v[40:41], 0
	v_mov_b64_e32 v[42:43], 0
	v_mov_b64_e32 v[44:45], 0
	v_mov_b64_e32 v[46:47], 0
	v_mov_b64_e32 v[48:49], 0
	v_mov_b64_e32 v[50:51], 0
	v_mov_b64_e32 v[52:53], 0
	v_mov_b64_e32 v[54:55], 0
	v_mov_b64_e32 v[56:57], 0
	v_mov_b64_e32 v[58:59], 0
	v_mov_b64_e32 v[60:61], 0
	v_mov_b64_e32 v[62:63], 0
	v_mov_b64_e32 v[64:65], 0
	v_mov_b64_e32 v[66:67], 0
	v_mov_b64_e32 v[68:69], 0
	v_mov_b64_e32 v[70:71], 0
	v_mov_b64_e32 v[72:73], 0
	v_mov_b64_e32 v[74:75], 0
	v_mov_b64_e32 v[76:77], 0
	v_mov_b64_e32 v[78:79], 0
	v_mov_b64_e32 v[80:81], 0
	v_mov_b64_e32 v[82:83], 0
	v_mov_b64_e32 v[84:85], 0
	v_mov_b64_e32 v[86:87], 0
	v_mov_b64_e32 v[88:89], 0
	v_mov_b64_e32 v[90:91], 0
	v_mov_b64_e32 v[92:93], 0
	v_mov_b64_e32 v[94:95], 0
	v_mov_b64_e32 v[96:97], 0
	v_mov_b64_e32 v[98:99], 0
	v_mov_b64_e32 v[100:101], 0
	v_mov_b64_e32 v[102:103], 0
	v_mov_b64_e32 v[104:105], 0
	v_mov_b64_e32 v[106:107], 0
	v_mov_b64_e32 v[108:109], 0
	v_mov_b64_e32 v[110:111], 0
	v_mov_b64_e32 v[112:113], 0
	v_mov_b64_e32 v[114:115], 0
	v_mov_b64_e32 v[116:117], 0
	v_mov_b64_e32 v[118:119], 0
	v_mov_b64_e32 v[120:121], 0
	v_mov_b64_e32 v[130:131], 0
	v_mov_b64_e32 v[132:133], 0
	v_mov_b64_e32 v[134:135], 0
	v_mov_b64_e32 v[136:137], 0
	s_andn2_b64 vcc, exec, s[46:47]
	s_cbranch_vccnz .LBB0_1846
